# grid barrier B3 with a single poll in flight (as the original spin)
# baseline (speedup 1.0000x reference)
.Lb3loop_0:
	global_load_dword v8, v17, s[18:19] sc1
	s_waitcnt vmcnt(0)
	v_cmp_ge_u32_e32 vcc, v8, v18
	s_cbranch_vccnz .Lb3done_0
	s_sleep 1
	s_add_u32 s20, s20, 1
	s_cmp_lt_u32 s20, 0x200000
	s_cbranch_scc1 .Lb3loop_0

.Lb3loop_8:
	global_load_dword v7, v16, s[18:19] sc1
	s_waitcnt vmcnt(0)
	v_cmp_ge_u32_e32 vcc, v7, v17
	s_cbranch_vccnz .Lb3done_8
	s_sleep 1
	s_add_u32 s20, s20, 1
	s_cmp_lt_u32 s20, 0x200000
	s_cbranch_scc1 .Lb3loop_8
